# adaLN GEMV in P0: k loop unrolled with 32 loads in flight per lane instead of 8 serial batches of 8
# baseline (speedup 1.0000x reference)
; #define lane (lane_now())
; __device__ __forceinline__ void p0_mod(const Params& p, LAS unsigned char* lds, int tid, int wave, int lane) {
;     ...
;         const int col = lane & 31, ks = wave * 2 + (lane >> 5), k0 = ks * 64, n = item * 32 + col;
;         float a0 = 0.f, a1 = 0.f, a2 = 0.f, a3 = 0.f;
; #pragma unroll 8
;         for (int kk = 0; kk < 64; ++kk) { const int k = k0 + kk; const float w = p.w_ada[(size_t)k * NMOD + n];
;             a0 += sc[k] * w; a1 += sc[1024 + k] * w; a2 += sc[2048 + k] * w; a3 += sc[3072 + k] * w; }
.LBB0_57:
	v_subrev_u32_e32 v126, s40, v10
	v_add_u32_e32 v126, 0xfffc1000, v126
	s_mov_b32 s98, s40
	s_mov_b32 s99, s41
	global_load_dword v128, v126, s[98:99]
	s_add_u32 s98, s98, 0x9000
	s_addc_u32 s99, s99, 0
	global_load_dword v130, v126, s[98:99]
	s_add_u32 s98, s98, 0x9000
	s_addc_u32 s99, s99, 0
	global_load_dword v132, v126, s[98:99]
	s_add_u32 s98, s98, 0x9000
	s_addc_u32 s99, s99, 0
	global_load_dword v134, v126, s[98:99]
	s_add_u32 s98, s98, 0x9000
	s_addc_u32 s99, s99, 0
	global_load_dword v136, v126, s[98:99]
	s_add_u32 s98, s98, 0x9000
	s_addc_u32 s99, s99, 0
	global_load_dword v138, v126, s[98:99]
	s_add_u32 s98, s98, 0x9000
	s_addc_u32 s99, s99, 0
	global_load_dword v140, v126, s[98:99]
	s_add_u32 s98, s98, 0x9000
	s_addc_u32 s99, s99, 0
	global_load_dword v142, v126, s[98:99]
	s_add_u32 s98, s98, 0x9000
	s_addc_u32 s99, s99, 0
	global_load_dword v144, v126, s[98:99]
	s_add_u32 s98, s98, 0x9000
	s_addc_u32 s99, s99, 0
	global_load_dword v146, v126, s[98:99]
	s_add_u32 s98, s98, 0x9000
	s_addc_u32 s99, s99, 0
	global_load_dword v148, v126, s[98:99]
	s_add_u32 s98, s98, 0x9000
	s_addc_u32 s99, s99, 0
	global_load_dword v150, v126, s[98:99]
	s_add_u32 s98, s98, 0x9000
	s_addc_u32 s99, s99, 0
	global_load_dword v152, v126, s[98:99]
	s_add_u32 s98, s98, 0x9000
	s_addc_u32 s99, s99, 0
	global_load_dword v154, v126, s[98:99]
	s_add_u32 s98, s98, 0x9000
	s_addc_u32 s99, s99, 0
	global_load_dword v156, v126, s[98:99]
	s_add_u32 s98, s98, 0x9000
	s_addc_u32 s99, s99, 0
	global_load_dword v158, v126, s[98:99]
	s_add_u32 s98, s98, 0x9000
	s_addc_u32 s99, s99, 0
	global_load_dword v160, v126, s[98:99]
	s_add_u32 s98, s98, 0x9000
	s_addc_u32 s99, s99, 0
	global_load_dword v162, v126, s[98:99]
	s_add_u32 s98, s98, 0x9000
	s_addc_u32 s99, s99, 0
	global_load_dword v164, v126, s[98:99]
	s_add_u32 s98, s98, 0x9000
	s_addc_u32 s99, s99, 0
	global_load_dword v166, v126, s[98:99]
	s_add_u32 s98, s98, 0x9000
	s_addc_u32 s99, s99, 0
	global_load_dword v168, v126, s[98:99]
	s_add_u32 s98, s98, 0x9000
	s_addc_u32 s99, s99, 0
	global_load_dword v170, v126, s[98:99]
	s_add_u32 s98, s98, 0x9000
	s_addc_u32 s99, s99, 0
	global_load_dword v172, v126, s[98:99]
	s_add_u32 s98, s98, 0x9000
	s_addc_u32 s99, s99, 0
	global_load_dword v174, v126, s[98:99]
	s_add_u32 s98, s98, 0x9000
	s_addc_u32 s99, s99, 0
	global_load_dword v176, v126, s[98:99]
	s_add_u32 s98, s98, 0x9000
	s_addc_u32 s99, s99, 0
	global_load_dword v178, v126, s[98:99]
	s_add_u32 s98, s98, 0x9000
	s_addc_u32 s99, s99, 0
	global_load_dword v180, v126, s[98:99]
	s_add_u32 s98, s98, 0x9000
	s_addc_u32 s99, s99, 0
	global_load_dword v182, v126, s[98:99]
	s_add_u32 s98, s98, 0x9000
	s_addc_u32 s99, s99, 0
	global_load_dword v184, v126, s[98:99]
	s_add_u32 s98, s98, 0x9000
	s_addc_u32 s99, s99, 0
	global_load_dword v186, v126, s[98:99]
	s_add_u32 s98, s98, 0x9000
	s_addc_u32 s99, s99, 0
	global_load_dword v188, v126, s[98:99]
	s_add_u32 s98, s98, 0x9000
	s_addc_u32 s99, s99, 0
	global_load_dword v190, v126, s[98:99]
	s_add_u32 s98, s98, 0x9000
	s_addc_u32 s99, s99, 0
	v_add_u32_e32 v9, s26, v2
	v_add_u32_e32 v19, 0x11100, v9
	v_add_u32_e32 v36, 0x11110, v9
	v_add_u32_e32 v40, 0x12110, v9
	v_add_u32_e32 v24, 0x12100, v9
	v_add_u32_e32 v28, 0x13100, v9
	v_add_u32_e32 v32, 0x14100, v9
	v_add_u32_e32 v44, 0x13110, v9
	v_add_u32_e32 v9, 0x14110, v9
	ds_read_b128 v[20:23], v19
	ds_read_b128 v[24:27], v24
	ds_read_b128 v[28:31], v28
	ds_read_b128 v[32:35], v32
	ds_read_b128 v[36:39], v36
	ds_read_b128 v[40:43], v40
	ds_read_b128 v[44:47], v44
	ds_read_b128 v[48:51], v9
	s_waitcnt lgkmcnt(5)
	v_mov_b32_e32 v68, v28
	v_mov_b32_e32 v69, v24
	v_mov_b32_e32 v70, v20
	s_waitcnt lgkmcnt(4)
	v_mov_b32_e32 v71, v32
	v_mov_b32_e32 v24, v29
	v_mov_b32_e32 v32, v21
	v_mov_b32_e32 v20, v30
	v_mov_b32_e32 v21, v26
	v_mov_b32_e32 v28, v22
	v_mov_b32_e32 v29, v34
	v_mov_b32_e32 v26, v31
	v_mov_b32_e32 v34, v23
	s_waitcnt lgkmcnt(1)
	v_mov_b32_e32 v22, v44
	v_mov_b32_e32 v23, v40
	v_mov_b32_e32 v30, v36
	s_waitcnt lgkmcnt(0)
	v_mov_b32_e32 v31, v48
	v_mov_b32_e32 v40, v45
	v_mov_b32_e32 v48, v37
	v_mov_b32_e32 v36, v46
	v_mov_b32_e32 v37, v42
	v_mov_b32_e32 v44, v38
	v_mov_b32_e32 v45, v50
	s_add_i32 s26, s26, 32
	v_mov_b32_e32 v42, v47
	v_mov_b32_e32 v50, v39
	s_waitcnt vmcnt(24)
	v_pk_fma_f32 v[14:15], v[128:129], v[68:69], v[14:15] op_sel_hi:[0,1,1]
	v_pk_fma_f32 v[12:13], v[128:129], v[70:71], v[12:13] op_sel_hi:[0,1,1]
	v_pk_fma_f32 v[14:15], v[130:131], v[24:25], v[14:15] op_sel_hi:[0,1,1]
	v_pk_fma_f32 v[12:13], v[130:131], v[32:33], v[12:13] op_sel_hi:[0,1,1]
	v_pk_fma_f32 v[14:15], v[132:133], v[20:21], v[14:15] op_sel_hi:[0,1,1]
	v_pk_fma_f32 v[12:13], v[132:133], v[28:29], v[12:13] op_sel_hi:[0,1,1]
	v_pk_fma_f32 v[14:15], v[134:135], v[26:27], v[14:15] op_sel_hi:[0,1,1]
	v_pk_fma_f32 v[12:13], v[134:135], v[34:35], v[12:13] op_sel_hi:[0,1,1]
	v_pk_fma_f32 v[14:15], v[136:137], v[22:23], v[14:15] op_sel_hi:[0,1,1]
	v_pk_fma_f32 v[12:13], v[136:137], v[30:31], v[12:13] op_sel_hi:[0,1,1]
	v_pk_fma_f32 v[14:15], v[138:139], v[40:41], v[14:15] op_sel_hi:[0,1,1]
	v_pk_fma_f32 v[12:13], v[138:139], v[48:49], v[12:13] op_sel_hi:[0,1,1]
	v_pk_fma_f32 v[14:15], v[140:141], v[36:37], v[14:15] op_sel_hi:[0,1,1]
	v_pk_fma_f32 v[12:13], v[140:141], v[44:45], v[12:13] op_sel_hi:[0,1,1]
	v_pk_fma_f32 v[14:15], v[142:143], v[42:43], v[14:15] op_sel_hi:[0,1,1]
	v_pk_fma_f32 v[12:13], v[142:143], v[50:51], v[12:13] op_sel_hi:[0,1,1]
	global_load_dword v128, v126, s[98:99]
	s_add_u32 s98, s98, 0x9000
	s_addc_u32 s99, s99, 0
	global_load_dword v130, v126, s[98:99]
	s_add_u32 s98, s98, 0x9000
	s_addc_u32 s99, s99, 0
	global_load_dword v132, v126, s[98:99]
	s_add_u32 s98, s98, 0x9000
	s_addc_u32 s99, s99, 0
	global_load_dword v134, v126, s[98:99]
	s_add_u32 s98, s98, 0x9000
	s_addc_u32 s99, s99, 0
	global_load_dword v136, v126, s[98:99]
	s_add_u32 s98, s98, 0x9000
	s_addc_u32 s99, s99, 0
	global_load_dword v138, v126, s[98:99]
	s_add_u32 s98, s98, 0x9000
	s_addc_u32 s99, s99, 0
	global_load_dword v140, v126, s[98:99]
	s_add_u32 s98, s98, 0x9000
	s_addc_u32 s99, s99, 0
	global_load_dword v142, v126, s[98:99]
	s_add_u32 s98, s98, 0x9000
	s_addc_u32 s99, s99, 0
	v_add_u32_e32 v9, s26, v2
	v_add_u32_e32 v19, 0x11100, v9
	v_add_u32_e32 v36, 0x11110, v9
	v_add_u32_e32 v40, 0x12110, v9
	v_add_u32_e32 v24, 0x12100, v9
	v_add_u32_e32 v28, 0x13100, v9
	v_add_u32_e32 v32, 0x14100, v9
	v_add_u32_e32 v44, 0x13110, v9
	v_add_u32_e32 v9, 0x14110, v9
	ds_read_b128 v[20:23], v19
	ds_read_b128 v[24:27], v24
	ds_read_b128 v[28:31], v28
	ds_read_b128 v[32:35], v32
	ds_read_b128 v[36:39], v36
	ds_read_b128 v[40:43], v40
	ds_read_b128 v[44:47], v44
	ds_read_b128 v[48:51], v9
	s_waitcnt lgkmcnt(5)
; __device__ __forceinline__ void p0_mod(const Params& p, LAS unsigned char* lds, int tid, int wave, int lane) {
;     ...
;         for (int kk = 0; kk < 64; ++kk) { const int k = k0 + kk; const float w = p.w_ada[(size_t)k * NMOD + n];
;             a0 += sc[k] * w; a1 += sc[1024 + k] * w; a2 += sc[2048 + k] * w; a3 += sc[3072 + k] * w; }
	v_mov_b32_e32 v68, v28
	v_mov_b32_e32 v69, v24
	v_mov_b32_e32 v70, v20
	s_waitcnt lgkmcnt(4)
	v_mov_b32_e32 v71, v32
	v_mov_b32_e32 v24, v29
	v_mov_b32_e32 v32, v21
	v_mov_b32_e32 v20, v30
	v_mov_b32_e32 v21, v26
	v_mov_b32_e32 v28, v22
	v_mov_b32_e32 v29, v34
	v_mov_b32_e32 v26, v31
	v_mov_b32_e32 v34, v23
	s_waitcnt lgkmcnt(1)
	v_mov_b32_e32 v22, v44
	v_mov_b32_e32 v23, v40
	v_mov_b32_e32 v30, v36
	s_waitcnt lgkmcnt(0)
	v_mov_b32_e32 v31, v48
	v_mov_b32_e32 v40, v45
	v_mov_b32_e32 v48, v37
	v_mov_b32_e32 v36, v46
	v_mov_b32_e32 v37, v42
	v_mov_b32_e32 v44, v38
	v_mov_b32_e32 v45, v50
	s_add_i32 s26, s26, 32
	v_mov_b32_e32 v42, v47
	v_mov_b32_e32 v50, v39
	s_waitcnt vmcnt(24)
	v_pk_fma_f32 v[14:15], v[144:145], v[68:69], v[14:15] op_sel_hi:[0,1,1]
	v_pk_fma_f32 v[12:13], v[144:145], v[70:71], v[12:13] op_sel_hi:[0,1,1]
	v_pk_fma_f32 v[14:15], v[146:147], v[24:25], v[14:15] op_sel_hi:[0,1,1]
	v_pk_fma_f32 v[12:13], v[146:147], v[32:33], v[12:13] op_sel_hi:[0,1,1]
	v_pk_fma_f32 v[14:15], v[148:149], v[20:21], v[14:15] op_sel_hi:[0,1,1]
	v_pk_fma_f32 v[12:13], v[148:149], v[28:29], v[12:13] op_sel_hi:[0,1,1]
	v_pk_fma_f32 v[14:15], v[150:151], v[26:27], v[14:15] op_sel_hi:[0,1,1]
	v_pk_fma_f32 v[12:13], v[150:151], v[34:35], v[12:13] op_sel_hi:[0,1,1]
	v_pk_fma_f32 v[14:15], v[152:153], v[22:23], v[14:15] op_sel_hi:[0,1,1]
	v_pk_fma_f32 v[12:13], v[152:153], v[30:31], v[12:13] op_sel_hi:[0,1,1]
	v_pk_fma_f32 v[14:15], v[154:155], v[40:41], v[14:15] op_sel_hi:[0,1,1]
	v_pk_fma_f32 v[12:13], v[154:155], v[48:49], v[12:13] op_sel_hi:[0,1,1]
	v_pk_fma_f32 v[14:15], v[156:157], v[36:37], v[14:15] op_sel_hi:[0,1,1]
	v_pk_fma_f32 v[12:13], v[156:157], v[44:45], v[12:13] op_sel_hi:[0,1,1]
	v_pk_fma_f32 v[14:15], v[158:159], v[42:43], v[14:15] op_sel_hi:[0,1,1]
	v_pk_fma_f32 v[12:13], v[158:159], v[50:51], v[12:13] op_sel_hi:[0,1,1]
	global_load_dword v144, v126, s[98:99]
	s_add_u32 s98, s98, 0x9000
	s_addc_u32 s99, s99, 0
	global_load_dword v146, v126, s[98:99]
	s_add_u32 s98, s98, 0x9000
	s_addc_u32 s99, s99, 0
	global_load_dword v148, v126, s[98:99]
	s_add_u32 s98, s98, 0x9000
	s_addc_u32 s99, s99, 0
	global_load_dword v150, v126, s[98:99]
	s_add_u32 s98, s98, 0x9000
	s_addc_u32 s99, s99, 0
	global_load_dword v152, v126, s[98:99]
	s_add_u32 s98, s98, 0x9000
	s_addc_u32 s99, s99, 0
	global_load_dword v154, v126, s[98:99]
	s_add_u32 s98, s98, 0x9000
	s_addc_u32 s99, s99, 0
	global_load_dword v156, v126, s[98:99]
	s_add_u32 s98, s98, 0x9000
	s_addc_u32 s99, s99, 0
	global_load_dword v158, v126, s[98:99]
	s_add_u32 s98, s98, 0x9000
	s_addc_u32 s99, s99, 0
	v_add_u32_e32 v9, s26, v2
	v_add_u32_e32 v19, 0x11100, v9
	v_add_u32_e32 v36, 0x11110, v9
	v_add_u32_e32 v40, 0x12110, v9
	v_add_u32_e32 v24, 0x12100, v9
	v_add_u32_e32 v28, 0x13100, v9
	v_add_u32_e32 v32, 0x14100, v9
	v_add_u32_e32 v44, 0x13110, v9
	v_add_u32_e32 v9, 0x14110, v9
	ds_read_b128 v[20:23], v19
	ds_read_b128 v[24:27], v24
	ds_read_b128 v[28:31], v28
	ds_read_b128 v[32:35], v32
	ds_read_b128 v[36:39], v36
	ds_read_b128 v[40:43], v40
	ds_read_b128 v[44:47], v44
	ds_read_b128 v[48:51], v9
	s_waitcnt lgkmcnt(5)
	v_mov_b32_e32 v68, v28
	v_mov_b32_e32 v69, v24
	v_mov_b32_e32 v70, v20
	s_waitcnt lgkmcnt(4)
	v_mov_b32_e32 v71, v32
	v_mov_b32_e32 v24, v29
	v_mov_b32_e32 v32, v21
	v_mov_b32_e32 v20, v30
	v_mov_b32_e32 v21, v26
	v_mov_b32_e32 v28, v22
	v_mov_b32_e32 v29, v34
	v_mov_b32_e32 v26, v31
	v_mov_b32_e32 v34, v23
	s_waitcnt lgkmcnt(1)
	v_mov_b32_e32 v22, v44
	v_mov_b32_e32 v23, v40
	v_mov_b32_e32 v30, v36
	s_waitcnt lgkmcnt(0)
	v_mov_b32_e32 v31, v48
	v_mov_b32_e32 v40, v45
	v_mov_b32_e32 v48, v37
	v_mov_b32_e32 v36, v46
	v_mov_b32_e32 v37, v42
	v_mov_b32_e32 v44, v38
	v_mov_b32_e32 v45, v50
	s_add_i32 s26, s26, 32
	v_mov_b32_e32 v42, v47
	v_mov_b32_e32 v50, v39
	s_waitcnt vmcnt(24)
	v_pk_fma_f32 v[14:15], v[160:161], v[68:69], v[14:15] op_sel_hi:[0,1,1]
	v_pk_fma_f32 v[12:13], v[160:161], v[70:71], v[12:13] op_sel_hi:[0,1,1]
	v_pk_fma_f32 v[14:15], v[162:163], v[24:25], v[14:15] op_sel_hi:[0,1,1]
	v_pk_fma_f32 v[12:13], v[162:163], v[32:33], v[12:13] op_sel_hi:[0,1,1]
	v_pk_fma_f32 v[14:15], v[164:165], v[20:21], v[14:15] op_sel_hi:[0,1,1]
	v_pk_fma_f32 v[12:13], v[164:165], v[28:29], v[12:13] op_sel_hi:[0,1,1]
	v_pk_fma_f32 v[14:15], v[166:167], v[26:27], v[14:15] op_sel_hi:[0,1,1]
	v_pk_fma_f32 v[12:13], v[166:167], v[34:35], v[12:13] op_sel_hi:[0,1,1]
	v_pk_fma_f32 v[14:15], v[168:169], v[22:23], v[14:15] op_sel_hi:[0,1,1]
	v_pk_fma_f32 v[12:13], v[168:169], v[30:31], v[12:13] op_sel_hi:[0,1,1]
	v_pk_fma_f32 v[14:15], v[170:171], v[40:41], v[14:15] op_sel_hi:[0,1,1]
	v_pk_fma_f32 v[12:13], v[170:171], v[48:49], v[12:13] op_sel_hi:[0,1,1]
	v_pk_fma_f32 v[14:15], v[172:173], v[36:37], v[14:15] op_sel_hi:[0,1,1]
	v_pk_fma_f32 v[12:13], v[172:173], v[44:45], v[12:13] op_sel_hi:[0,1,1]
	v_pk_fma_f32 v[14:15], v[174:175], v[42:43], v[14:15] op_sel_hi:[0,1,1]
	v_pk_fma_f32 v[12:13], v[174:175], v[50:51], v[12:13] op_sel_hi:[0,1,1]
	global_load_dword v160, v126, s[98:99]
	s_add_u32 s98, s98, 0x9000
	s_addc_u32 s99, s99, 0
	global_load_dword v162, v126, s[98:99]
	s_add_u32 s98, s98, 0x9000
	s_addc_u32 s99, s99, 0
	global_load_dword v164, v126, s[98:99]
	s_add_u32 s98, s98, 0x9000
	s_addc_u32 s99, s99, 0
	global_load_dword v166, v126, s[98:99]
	s_add_u32 s98, s98, 0x9000
	s_addc_u32 s99, s99, 0
	global_load_dword v168, v126, s[98:99]
	s_add_u32 s98, s98, 0x9000
	s_addc_u32 s99, s99, 0
	global_load_dword v170, v126, s[98:99]
	s_add_u32 s98, s98, 0x9000
	s_addc_u32 s99, s99, 0
	global_load_dword v172, v126, s[98:99]
	s_add_u32 s98, s98, 0x9000
	s_addc_u32 s99, s99, 0
	global_load_dword v174, v126, s[98:99]
	s_add_u32 s98, s98, 0x9000
	s_addc_u32 s99, s99, 0
	v_add_u32_e32 v9, s26, v2
	v_add_u32_e32 v19, 0x11100, v9
	v_add_u32_e32 v36, 0x11110, v9
	v_add_u32_e32 v40, 0x12110, v9
	v_add_u32_e32 v24, 0x12100, v9
	v_add_u32_e32 v28, 0x13100, v9
	v_add_u32_e32 v32, 0x14100, v9
	v_add_u32_e32 v44, 0x13110, v9
	v_add_u32_e32 v9, 0x14110, v9
	ds_read_b128 v[20:23], v19
	ds_read_b128 v[24:27], v24
	ds_read_b128 v[28:31], v28
	ds_read_b128 v[32:35], v32
	ds_read_b128 v[36:39], v36
	ds_read_b128 v[40:43], v40
	ds_read_b128 v[44:47], v44
	ds_read_b128 v[48:51], v9
	s_waitcnt lgkmcnt(5)
; __device__ __forceinline__ void p0_mod(const Params& p, LAS unsigned char* lds, int tid, int wave, int lane) {
;     ...
;         for (int kk = 0; kk < 64; ++kk) { const int k = k0 + kk; const float w = p.w_ada[(size_t)k * NMOD + n];
;             a0 += sc[k] * w; a1 += sc[1024 + k] * w; a2 += sc[2048 + k] * w; a3 += sc[3072 + k] * w; }
	v_mov_b32_e32 v68, v28
	v_mov_b32_e32 v69, v24
	v_mov_b32_e32 v70, v20
	s_waitcnt lgkmcnt(4)
	v_mov_b32_e32 v71, v32
	v_mov_b32_e32 v24, v29
	v_mov_b32_e32 v32, v21
	v_mov_b32_e32 v20, v30
	v_mov_b32_e32 v21, v26
	v_mov_b32_e32 v28, v22
	v_mov_b32_e32 v29, v34
	v_mov_b32_e32 v26, v31
	v_mov_b32_e32 v34, v23
	s_waitcnt lgkmcnt(1)
	v_mov_b32_e32 v22, v44
	v_mov_b32_e32 v23, v40
	v_mov_b32_e32 v30, v36
	s_waitcnt lgkmcnt(0)
	v_mov_b32_e32 v31, v48
	v_mov_b32_e32 v40, v45
	v_mov_b32_e32 v48, v37
	v_mov_b32_e32 v36, v46
	v_mov_b32_e32 v37, v42
	v_mov_b32_e32 v44, v38
	v_mov_b32_e32 v45, v50
	s_add_i32 s26, s26, 32
	v_mov_b32_e32 v42, v47
	v_mov_b32_e32 v50, v39
	s_waitcnt vmcnt(24)
	v_pk_fma_f32 v[14:15], v[176:177], v[68:69], v[14:15] op_sel_hi:[0,1,1]
	v_pk_fma_f32 v[12:13], v[176:177], v[70:71], v[12:13] op_sel_hi:[0,1,1]
	v_pk_fma_f32 v[14:15], v[178:179], v[24:25], v[14:15] op_sel_hi:[0,1,1]
	v_pk_fma_f32 v[12:13], v[178:179], v[32:33], v[12:13] op_sel_hi:[0,1,1]
	v_pk_fma_f32 v[14:15], v[180:181], v[20:21], v[14:15] op_sel_hi:[0,1,1]
	v_pk_fma_f32 v[12:13], v[180:181], v[28:29], v[12:13] op_sel_hi:[0,1,1]
	v_pk_fma_f32 v[14:15], v[182:183], v[26:27], v[14:15] op_sel_hi:[0,1,1]
	v_pk_fma_f32 v[12:13], v[182:183], v[34:35], v[12:13] op_sel_hi:[0,1,1]
	v_pk_fma_f32 v[14:15], v[184:185], v[22:23], v[14:15] op_sel_hi:[0,1,1]
	v_pk_fma_f32 v[12:13], v[184:185], v[30:31], v[12:13] op_sel_hi:[0,1,1]
	v_pk_fma_f32 v[14:15], v[186:187], v[40:41], v[14:15] op_sel_hi:[0,1,1]
	v_pk_fma_f32 v[12:13], v[186:187], v[48:49], v[12:13] op_sel_hi:[0,1,1]
	v_pk_fma_f32 v[14:15], v[188:189], v[36:37], v[14:15] op_sel_hi:[0,1,1]
	v_pk_fma_f32 v[12:13], v[188:189], v[44:45], v[12:13] op_sel_hi:[0,1,1]
	v_pk_fma_f32 v[14:15], v[190:191], v[42:43], v[14:15] op_sel_hi:[0,1,1]
	v_pk_fma_f32 v[12:13], v[190:191], v[50:51], v[12:13] op_sel_hi:[0,1,1]
	global_load_dword v176, v126, s[98:99]
	s_add_u32 s98, s98, 0x9000
	s_addc_u32 s99, s99, 0
	global_load_dword v178, v126, s[98:99]
	s_add_u32 s98, s98, 0x9000
	s_addc_u32 s99, s99, 0
	global_load_dword v180, v126, s[98:99]
	s_add_u32 s98, s98, 0x9000
	s_addc_u32 s99, s99, 0
	global_load_dword v182, v126, s[98:99]
	s_add_u32 s98, s98, 0x9000
	s_addc_u32 s99, s99, 0
	global_load_dword v184, v126, s[98:99]
	s_add_u32 s98, s98, 0x9000
	s_addc_u32 s99, s99, 0
	global_load_dword v186, v126, s[98:99]
	s_add_u32 s98, s98, 0x9000
	s_addc_u32 s99, s99, 0
	global_load_dword v188, v126, s[98:99]
	s_add_u32 s98, s98, 0x9000
	s_addc_u32 s99, s99, 0
	global_load_dword v190, v126, s[98:99]
	s_add_u32 s98, s98, 0x9000
	s_addc_u32 s99, s99, 0
	v_add_u32_e32 v9, s26, v2
	v_add_u32_e32 v19, 0x11100, v9
	v_add_u32_e32 v36, 0x11110, v9
	v_add_u32_e32 v40, 0x12110, v9
	v_add_u32_e32 v24, 0x12100, v9
	v_add_u32_e32 v28, 0x13100, v9
	v_add_u32_e32 v32, 0x14100, v9
	v_add_u32_e32 v44, 0x13110, v9
	v_add_u32_e32 v9, 0x14110, v9
	ds_read_b128 v[20:23], v19
	ds_read_b128 v[24:27], v24
	ds_read_b128 v[28:31], v28
	ds_read_b128 v[32:35], v32
	ds_read_b128 v[36:39], v36
	ds_read_b128 v[40:43], v40
	ds_read_b128 v[44:47], v44
	ds_read_b128 v[48:51], v9
	s_waitcnt lgkmcnt(5)
	v_mov_b32_e32 v68, v28
	v_mov_b32_e32 v69, v24
	v_mov_b32_e32 v70, v20
	s_waitcnt lgkmcnt(4)
	v_mov_b32_e32 v71, v32
	v_mov_b32_e32 v24, v29
	v_mov_b32_e32 v32, v21
	v_mov_b32_e32 v20, v30
	v_mov_b32_e32 v21, v26
	v_mov_b32_e32 v28, v22
	v_mov_b32_e32 v29, v34
	v_mov_b32_e32 v26, v31
	v_mov_b32_e32 v34, v23
	s_waitcnt lgkmcnt(1)
	v_mov_b32_e32 v22, v44
	v_mov_b32_e32 v23, v40
	v_mov_b32_e32 v30, v36
	s_waitcnt lgkmcnt(0)
	v_mov_b32_e32 v31, v48
	v_mov_b32_e32 v40, v45
	v_mov_b32_e32 v48, v37
	v_mov_b32_e32 v36, v46
	v_mov_b32_e32 v37, v42
	v_mov_b32_e32 v44, v38
	v_mov_b32_e32 v45, v50
	s_add_i32 s26, s26, 32
	v_mov_b32_e32 v42, v47
	v_mov_b32_e32 v50, v39
	s_waitcnt vmcnt(24)
	v_pk_fma_f32 v[14:15], v[128:129], v[68:69], v[14:15] op_sel_hi:[0,1,1]
	v_pk_fma_f32 v[12:13], v[128:129], v[70:71], v[12:13] op_sel_hi:[0,1,1]
	v_pk_fma_f32 v[14:15], v[130:131], v[24:25], v[14:15] op_sel_hi:[0,1,1]
	v_pk_fma_f32 v[12:13], v[130:131], v[32:33], v[12:13] op_sel_hi:[0,1,1]
	v_pk_fma_f32 v[14:15], v[132:133], v[20:21], v[14:15] op_sel_hi:[0,1,1]
	v_pk_fma_f32 v[12:13], v[132:133], v[28:29], v[12:13] op_sel_hi:[0,1,1]
	v_pk_fma_f32 v[14:15], v[134:135], v[26:27], v[14:15] op_sel_hi:[0,1,1]
	v_pk_fma_f32 v[12:13], v[134:135], v[34:35], v[12:13] op_sel_hi:[0,1,1]
	v_pk_fma_f32 v[14:15], v[136:137], v[22:23], v[14:15] op_sel_hi:[0,1,1]
	v_pk_fma_f32 v[12:13], v[136:137], v[30:31], v[12:13] op_sel_hi:[0,1,1]
	v_pk_fma_f32 v[14:15], v[138:139], v[40:41], v[14:15] op_sel_hi:[0,1,1]
	v_pk_fma_f32 v[12:13], v[138:139], v[48:49], v[12:13] op_sel_hi:[0,1,1]
	v_pk_fma_f32 v[14:15], v[140:141], v[36:37], v[14:15] op_sel_hi:[0,1,1]
	v_pk_fma_f32 v[12:13], v[140:141], v[44:45], v[12:13] op_sel_hi:[0,1,1]
	v_pk_fma_f32 v[14:15], v[142:143], v[42:43], v[14:15] op_sel_hi:[0,1,1]
	v_pk_fma_f32 v[12:13], v[142:143], v[50:51], v[12:13] op_sel_hi:[0,1,1]
	v_add_u32_e32 v9, s26, v2
	v_add_u32_e32 v19, 0x11100, v9
	v_add_u32_e32 v36, 0x11110, v9
	v_add_u32_e32 v40, 0x12110, v9
	v_add_u32_e32 v24, 0x12100, v9
	v_add_u32_e32 v28, 0x13100, v9
	v_add_u32_e32 v32, 0x14100, v9
	v_add_u32_e32 v44, 0x13110, v9
	v_add_u32_e32 v9, 0x14110, v9
	ds_read_b128 v[20:23], v19
	ds_read_b128 v[24:27], v24
	ds_read_b128 v[28:31], v28
	ds_read_b128 v[32:35], v32
	ds_read_b128 v[36:39], v36
	ds_read_b128 v[40:43], v40
	ds_read_b128 v[44:47], v44
	ds_read_b128 v[48:51], v9
	s_waitcnt lgkmcnt(5)
	v_mov_b32_e32 v68, v28
	v_mov_b32_e32 v69, v24
	v_mov_b32_e32 v70, v20
	s_waitcnt lgkmcnt(4)
; __device__ __forceinline__ void p0_mod(const Params& p, LAS unsigned char* lds, int tid, int wave, int lane) {
;     ...
;         for (int kk = 0; kk < 64; ++kk) { const int k = k0 + kk; const float w = p.w_ada[(size_t)k * NMOD + n];
;             a0 += sc[k] * w; a1 += sc[1024 + k] * w; a2 += sc[2048 + k] * w; a3 += sc[3072 + k] * w; }
;         red[(ks * 4 + 0) * 32 + col] = a0; red[(ks * 4 + 1) * 32 + col] = a1; red[(ks * 4 + 2) * 32 + col] = a2; red[(ks * 4 + 3) * 32 + col] = a3;
;         __syncthreads();
	v_mov_b32_e32 v71, v32
	v_mov_b32_e32 v24, v29
	v_mov_b32_e32 v32, v21
	v_mov_b32_e32 v20, v30
	v_mov_b32_e32 v21, v26
	v_mov_b32_e32 v28, v22
	v_mov_b32_e32 v29, v34
	v_mov_b32_e32 v26, v31
	v_mov_b32_e32 v34, v23
	s_waitcnt lgkmcnt(1)
	v_mov_b32_e32 v22, v44
	v_mov_b32_e32 v23, v40
	v_mov_b32_e32 v30, v36
	s_waitcnt lgkmcnt(0)
	v_mov_b32_e32 v31, v48
	v_mov_b32_e32 v40, v45
	v_mov_b32_e32 v48, v37
	v_mov_b32_e32 v36, v46
	v_mov_b32_e32 v37, v42
	v_mov_b32_e32 v44, v38
	v_mov_b32_e32 v45, v50
	s_add_i32 s26, s26, 32
	v_mov_b32_e32 v42, v47
	v_mov_b32_e32 v50, v39
	s_waitcnt vmcnt(16)
	v_pk_fma_f32 v[14:15], v[144:145], v[68:69], v[14:15] op_sel_hi:[0,1,1]
	v_pk_fma_f32 v[12:13], v[144:145], v[70:71], v[12:13] op_sel_hi:[0,1,1]
	v_pk_fma_f32 v[14:15], v[146:147], v[24:25], v[14:15] op_sel_hi:[0,1,1]
	v_pk_fma_f32 v[12:13], v[146:147], v[32:33], v[12:13] op_sel_hi:[0,1,1]
	v_pk_fma_f32 v[14:15], v[148:149], v[20:21], v[14:15] op_sel_hi:[0,1,1]
	v_pk_fma_f32 v[12:13], v[148:149], v[28:29], v[12:13] op_sel_hi:[0,1,1]
	v_pk_fma_f32 v[14:15], v[150:151], v[26:27], v[14:15] op_sel_hi:[0,1,1]
	v_pk_fma_f32 v[12:13], v[150:151], v[34:35], v[12:13] op_sel_hi:[0,1,1]
	v_pk_fma_f32 v[14:15], v[152:153], v[22:23], v[14:15] op_sel_hi:[0,1,1]
	v_pk_fma_f32 v[12:13], v[152:153], v[30:31], v[12:13] op_sel_hi:[0,1,1]
	v_pk_fma_f32 v[14:15], v[154:155], v[40:41], v[14:15] op_sel_hi:[0,1,1]
	v_pk_fma_f32 v[12:13], v[154:155], v[48:49], v[12:13] op_sel_hi:[0,1,1]
	v_pk_fma_f32 v[14:15], v[156:157], v[36:37], v[14:15] op_sel_hi:[0,1,1]
	v_pk_fma_f32 v[12:13], v[156:157], v[44:45], v[12:13] op_sel_hi:[0,1,1]
	v_pk_fma_f32 v[14:15], v[158:159], v[42:43], v[14:15] op_sel_hi:[0,1,1]
	v_pk_fma_f32 v[12:13], v[158:159], v[50:51], v[12:13] op_sel_hi:[0,1,1]
	v_add_u32_e32 v9, s26, v2
	v_add_u32_e32 v19, 0x11100, v9
	v_add_u32_e32 v36, 0x11110, v9
	v_add_u32_e32 v40, 0x12110, v9
	v_add_u32_e32 v24, 0x12100, v9
	v_add_u32_e32 v28, 0x13100, v9
	v_add_u32_e32 v32, 0x14100, v9
	v_add_u32_e32 v44, 0x13110, v9
	v_add_u32_e32 v9, 0x14110, v9
	ds_read_b128 v[20:23], v19
	ds_read_b128 v[24:27], v24
	ds_read_b128 v[28:31], v28
	ds_read_b128 v[32:35], v32
	ds_read_b128 v[36:39], v36
	ds_read_b128 v[40:43], v40
	ds_read_b128 v[44:47], v44
	ds_read_b128 v[48:51], v9
	s_waitcnt lgkmcnt(5)
	v_mov_b32_e32 v68, v28
	v_mov_b32_e32 v69, v24
	v_mov_b32_e32 v70, v20
	s_waitcnt lgkmcnt(4)
	v_mov_b32_e32 v71, v32
	v_mov_b32_e32 v24, v29
	v_mov_b32_e32 v32, v21
	v_mov_b32_e32 v20, v30
	v_mov_b32_e32 v21, v26
	v_mov_b32_e32 v28, v22
	v_mov_b32_e32 v29, v34
	v_mov_b32_e32 v26, v31
	v_mov_b32_e32 v34, v23
	s_waitcnt lgkmcnt(1)
	v_mov_b32_e32 v22, v44
	v_mov_b32_e32 v23, v40
	v_mov_b32_e32 v30, v36
	s_waitcnt lgkmcnt(0)
	v_mov_b32_e32 v31, v48
	v_mov_b32_e32 v40, v45
	v_mov_b32_e32 v48, v37
	v_mov_b32_e32 v36, v46
	v_mov_b32_e32 v37, v42
	v_mov_b32_e32 v44, v38
	v_mov_b32_e32 v45, v50
	s_add_i32 s26, s26, 32
	v_mov_b32_e32 v42, v47
	v_mov_b32_e32 v50, v39
	s_waitcnt vmcnt(8)
	v_pk_fma_f32 v[14:15], v[160:161], v[68:69], v[14:15] op_sel_hi:[0,1,1]
	v_pk_fma_f32 v[12:13], v[160:161], v[70:71], v[12:13] op_sel_hi:[0,1,1]
	v_pk_fma_f32 v[14:15], v[162:163], v[24:25], v[14:15] op_sel_hi:[0,1,1]
	v_pk_fma_f32 v[12:13], v[162:163], v[32:33], v[12:13] op_sel_hi:[0,1,1]
	v_pk_fma_f32 v[14:15], v[164:165], v[20:21], v[14:15] op_sel_hi:[0,1,1]
	v_pk_fma_f32 v[12:13], v[164:165], v[28:29], v[12:13] op_sel_hi:[0,1,1]
	v_pk_fma_f32 v[14:15], v[166:167], v[26:27], v[14:15] op_sel_hi:[0,1,1]
	v_pk_fma_f32 v[12:13], v[166:167], v[34:35], v[12:13] op_sel_hi:[0,1,1]
	v_pk_fma_f32 v[14:15], v[168:169], v[22:23], v[14:15] op_sel_hi:[0,1,1]
	v_pk_fma_f32 v[12:13], v[168:169], v[30:31], v[12:13] op_sel_hi:[0,1,1]
	v_pk_fma_f32 v[14:15], v[170:171], v[40:41], v[14:15] op_sel_hi:[0,1,1]
	v_pk_fma_f32 v[12:13], v[170:171], v[48:49], v[12:13] op_sel_hi:[0,1,1]
	v_pk_fma_f32 v[14:15], v[172:173], v[36:37], v[14:15] op_sel_hi:[0,1,1]
	v_pk_fma_f32 v[12:13], v[172:173], v[44:45], v[12:13] op_sel_hi:[0,1,1]
	v_pk_fma_f32 v[14:15], v[174:175], v[42:43], v[14:15] op_sel_hi:[0,1,1]
	v_pk_fma_f32 v[12:13], v[174:175], v[50:51], v[12:13] op_sel_hi:[0,1,1]
	v_add_u32_e32 v9, s26, v2
	v_add_u32_e32 v19, 0x11100, v9
	v_add_u32_e32 v36, 0x11110, v9
	v_add_u32_e32 v40, 0x12110, v9
	v_add_u32_e32 v24, 0x12100, v9
	v_add_u32_e32 v28, 0x13100, v9
	v_add_u32_e32 v32, 0x14100, v9
	v_add_u32_e32 v44, 0x13110, v9
	v_add_u32_e32 v9, 0x14110, v9
	ds_read_b128 v[20:23], v19
	ds_read_b128 v[24:27], v24
	ds_read_b128 v[28:31], v28
	ds_read_b128 v[32:35], v32
	ds_read_b128 v[36:39], v36
	ds_read_b128 v[40:43], v40
	ds_read_b128 v[44:47], v44
	ds_read_b128 v[48:51], v9
	s_waitcnt lgkmcnt(5)
	v_mov_b32_e32 v68, v28
	v_mov_b32_e32 v69, v24
	v_mov_b32_e32 v70, v20
	s_waitcnt lgkmcnt(4)
	v_mov_b32_e32 v71, v32
	v_mov_b32_e32 v24, v29
	v_mov_b32_e32 v32, v21
	v_mov_b32_e32 v20, v30
	v_mov_b32_e32 v21, v26
	v_mov_b32_e32 v28, v22
	v_mov_b32_e32 v29, v34
	v_mov_b32_e32 v26, v31
	v_mov_b32_e32 v34, v23
	s_waitcnt lgkmcnt(1)
	v_mov_b32_e32 v22, v44
	v_mov_b32_e32 v23, v40
	v_mov_b32_e32 v30, v36
	s_waitcnt lgkmcnt(0)
	v_mov_b32_e32 v31, v48
	v_mov_b32_e32 v40, v45
	v_mov_b32_e32 v48, v37
	v_mov_b32_e32 v36, v46
	v_mov_b32_e32 v37, v42
	v_mov_b32_e32 v44, v38
	v_mov_b32_e32 v45, v50
	s_add_i32 s26, s26, 32
	v_mov_b32_e32 v42, v47
	v_mov_b32_e32 v50, v39
	s_waitcnt vmcnt(0)
	v_pk_fma_f32 v[14:15], v[176:177], v[68:69], v[14:15] op_sel_hi:[0,1,1]
	v_pk_fma_f32 v[12:13], v[176:177], v[70:71], v[12:13] op_sel_hi:[0,1,1]
	v_pk_fma_f32 v[14:15], v[178:179], v[24:25], v[14:15] op_sel_hi:[0,1,1]
	v_pk_fma_f32 v[12:13], v[178:179], v[32:33], v[12:13] op_sel_hi:[0,1,1]
	v_pk_fma_f32 v[14:15], v[180:181], v[20:21], v[14:15] op_sel_hi:[0,1,1]
	v_pk_fma_f32 v[12:13], v[180:181], v[28:29], v[12:13] op_sel_hi:[0,1,1]
	v_pk_fma_f32 v[14:15], v[182:183], v[26:27], v[14:15] op_sel_hi:[0,1,1]
	v_pk_fma_f32 v[12:13], v[182:183], v[34:35], v[12:13] op_sel_hi:[0,1,1]
	v_pk_fma_f32 v[14:15], v[184:185], v[22:23], v[14:15] op_sel_hi:[0,1,1]
	v_pk_fma_f32 v[12:13], v[184:185], v[30:31], v[12:13] op_sel_hi:[0,1,1]
	v_pk_fma_f32 v[14:15], v[186:187], v[40:41], v[14:15] op_sel_hi:[0,1,1]
	v_pk_fma_f32 v[12:13], v[186:187], v[48:49], v[12:13] op_sel_hi:[0,1,1]
	v_pk_fma_f32 v[14:15], v[188:189], v[36:37], v[14:15] op_sel_hi:[0,1,1]
	v_pk_fma_f32 v[12:13], v[188:189], v[44:45], v[12:13] op_sel_hi:[0,1,1]
	v_pk_fma_f32 v[14:15], v[190:191], v[42:43], v[14:15] op_sel_hi:[0,1,1]
	v_pk_fma_f32 v[12:13], v[190:191], v[50:51], v[12:13] op_sel_hi:[0,1,1]
	ds_write2_b32 v17, v12, v15 offset1:32
	ds_write2_b32 v17, v14, v13 offset0:64 offset1:96
	s_waitcnt lgkmcnt(0)
	s_barrier
; __device__ __forceinline__ void p0_mod(const Params& p, LAS unsigned char* lds, int tid, int wave, int lane) {
;     ...
;         if (tid < 128) { const int b = tid >> 5, cc = tid & 31; float s = p.b_ada[item * 32 + cc];
; #pragma unroll
;             for (int q = 0; q < 16; ++q) s += red[(q * 4 + b) * 32 + cc];
;             mod[(size_t)b * NMOD + item * 32 + cc] = s; }
;         __syncthreads();
	s_and_saveexec_b64 s[4:5], s[0:1]
	s_cbranch_execz .LBB0_55
	s_lshl_b32 s26, s25, 5
	v_or_b32_e32 v10, s26, v16
	v_ashrrev_i32_e32 v11, 31, v10
	v_lshl_add_u64 v[10:11], v[10:11], 2, s[42:43]
	global_load_dword v9, v[10:11], off
	ds_read2st64_b32 v[10:11], v18 offset1:2
	ds_read2st64_b32 v[12:13], v18 offset0:4 offset1:6
	ds_read2st64_b32 v[14:15], v18 offset0:8 offset1:10
	ds_read2st64_b32 v[20:21], v18 offset0:12 offset1:14
	ds_read2st64_b32 v[22:23], v18 offset0:16 offset1:18
	ds_read2st64_b32 v[24:25], v18 offset0:20 offset1:22
	ds_read2st64_b32 v[26:27], v18 offset0:24 offset1:26
	ds_read2st64_b32 v[28:29], v18 offset0:28 offset1:30
	s_ashr_i32 s27, s26, 31
	s_waitcnt vmcnt(0) lgkmcnt(7)
	v_add_f32_e32 v9, v9, v10
	v_add_f32_e32 v9, v9, v11
	s_waitcnt lgkmcnt(6)
	v_add_f32_e32 v9, v9, v12
	v_add_f32_e32 v9, v9, v13
	s_waitcnt lgkmcnt(5)
	v_add_f32_e32 v9, v9, v14
	v_add_f32_e32 v9, v9, v15
	s_waitcnt lgkmcnt(4)
	v_add_f32_e32 v9, v9, v20
	v_add_f32_e32 v9, v9, v21
	s_waitcnt lgkmcnt(3)
	v_add_f32_e32 v9, v9, v22
	v_add_f32_e32 v9, v9, v23
	s_waitcnt lgkmcnt(2)
	v_add_f32_e32 v9, v9, v24
	v_add_f32_e32 v9, v9, v25
	s_waitcnt lgkmcnt(1)
	v_add_f32_e32 v9, v9, v26
	v_add_f32_e32 v9, v9, v27
	s_waitcnt lgkmcnt(0)
	v_add_f32_e32 v9, v9, v28
	v_add_f32_e32 v9, v9, v29
	v_lshl_add_u64 v[10:11], s[26:27], 2, v[4:5]
	global_store_dword v[10:11], v9, off
	s_branch .LBB0_55
